# FoX prologue: c2-image loads issued before K0/V0/K1/K2 DMA and the queue atomic; image wait counts only those loads; queue counter published after step 0
# baseline (speedup 1.0000x reference)
.LBB0_276:
	v_mov_b32_e32 v0, s0
	s_waitcnt lgkmcnt(0)
	s_barrier
	ds_read_b32 v0, v0
	s_add_i32 s52, s10, 0x100
	s_ashr_i32 s47, s52, 6
	v_add_u32_e32 v19, 0x200, v181
	v_add_u32_e32 v18, 0x400, v181
	s_waitcnt lgkmcnt(0)
	v_readfirstlane_b32 s1, v0
	s_lshl_b32 s84, s1, 7
	s_lshl_b32 s50, s1, 1
	s_ashr_i32 s85, s84, 31
	s_sub_i32 s78, s47, s50
	s_lshl_b64 s[6:7], s[84:85], 2
	s_add_u32 s10, s39, s6
	s_addc_u32 s11, s54, s7
	s_lshl_b32 s33, s78, 4
	v_cmp_gt_i32_e64 s[8:9], s33, v19
	v_cmp_gt_i32_e64 s[6:7], s33, v18
	v_add_u32_e32 v17, 0x600, v181
	v_cndmask_b32_e64 v2, v181, v19, s[8:9]
	v_lshlrev_b32_e32 v2, 2, v2
	v_ashrrev_i32_e32 v3, 31, v2
	v_lshl_add_u64 v[8:9], v[2:3], 2, s[10:11]
	v_cndmask_b32_e64 v2, v181, v18, s[6:7]
	v_lshlrev_b32_e32 v2, 2, v2
	v_ashrrev_i32_e32 v3, 31, v2
	v_cmp_gt_i32_e32 vcc, s33, v17
	v_lshl_add_u64 v[4:5], v[2:3], 2, s[10:11]
	v_lshlrev_b32_e32 v0, 2, v181
	v_cndmask_b32_e32 v2, v181, v17, vcc
	v_lshlrev_b32_e32 v2, 2, v2
	v_ashrrev_i32_e32 v1, 31, v0
	v_ashrrev_i32_e32 v3, 31, v2
	v_lshl_add_u64 v[0:1], v[0:1], 2, s[10:11]
	v_lshl_add_u64 v[2:3], v[2:3], 2, s[10:11]
	global_load_dwordx4 v[12:15], v[0:1], off
	s_nop 0
	global_load_dwordx4 v[0:3], v[2:3], off
	s_nop 0
	global_load_dwordx4 v[4:7], v[4:5], off
	s_nop 0
	global_load_dwordx4 v[8:11], v[8:9], off
	s_lshl_b32 s1, s1, 2
	s_add_i32 s29, s1, 0
	v_lshlrev_b32_e32 v33, 4, v181
	s_add_i32 s29, s29, 0x1c800
	v_cmp_gt_i32_e64 s[10:11], s33, v181
	v_writelane_b32 v241, s16, 30
	v_writelane_b32 v241, s17, 31
	v_writelane_b32 v241, s18, 32
	v_writelane_b32 v241, s19, 33
	v_writelane_b32 v241, s20, 34
	v_writelane_b32 v241, s21, 35
	s_lshl_b64 s[16:17], s[30:31], 24
	s_add_u32 s18, s14, s16
	s_addc_u32 s19, s15, s17
	s_add_u32 s18, s18, s92
	s_addc_u32 s19, s19, s93
	s_add_u32 s20, s71, s16
	s_addc_u32 s21, s72, s17
	s_add_u32 s20, s20, s92
	s_addc_u32 s21, s21, s93
	s_mov_b32 s100, s50
	s_ashr_i32 s101, s50, 31
	s_lshl_b64 s[16:17], s[100:101], 17
	s_add_u32 s18, s18, s16
	s_addc_u32 s19, s19, s17
	s_add_u32 s20, s20, s16
	s_addc_u32 s21, s21, s17
	s_lshl_b32 s100, s69, 4
	v_lshl_add_u32 v198, v178, 11, s100
	v_lshrrev_b32_e32 v199, 2, v178
	v_and_or_b32 v199, s100, 48, v199
	s_ashr_i32 s101, s34, 8
	s_lshl_b32 s101, s101, 5
	v_lshl_add_u32 v199, v199, 10, s101
	v_lshlrev_b32_e32 v200, 3, v32
	v_and_b32_e32 v200, 24, v200
	v_or_b32_e32 v199, v199, v200
	v_lshlrev_b32_e32 v199, 1, v199
	s_lshl_b32 s100, s69, 10
	s_mov_b32 s101, m0
	s_mov_b32 m0, s100
	s_nop 0
	global_load_lds_dwordx4 v198, s[18:19]
	s_add_i32 m0, s100, 0x6000
	s_nop 0
	global_load_lds_dwordx4 v199, s[20:21]
	s_add_u32 s16, s18, 0x20000
	s_addc_u32 s17, s19, 0
	s_add_i32 m0, s100, 0x2000
	s_nop 0
	global_load_lds_dwordx4 v198, s[16:17]
	s_add_u32 s16, s18, 0x40000
	s_addc_u32 s17, s19, 0
	s_add_i32 m0, s100, 0x4000
	s_nop 0
	global_load_lds_dwordx4 v198, s[16:17]
	s_mov_b32 m0, s101
	v_mov_b32_e32 v201, 0
	v_cmp_eq_u32_e64 s[16:17], 0, v181
	s_and_saveexec_b64 s[16:17], s[16:17]
	s_cbranch_execz .Lmy_fox_noq
	v_mov_b32_e32 v201, 1
	global_atomic_add v201, v101, v201, s[58:59] sc0
.Lmy_fox_noq:
	s_or_b64 exec, exec, s[16:17]
	v_readlane_b32 s16, v241, 30
	v_readlane_b32 s17, v241, 31
	v_readlane_b32 s18, v241, 32
	v_readlane_b32 s19, v241, 33
	v_readlane_b32 s20, v241, 34
	v_readlane_b32 s21, v241, 35
	s_cmp_lg_u32 s34, 0
	s_cbranch_scc1 .Lmy_fox_w4
	s_waitcnt vmcnt(5)
	s_branch .Lmy_fox_wd
.Lmy_fox_w4:
	s_waitcnt vmcnt(4)

.LBB0_286:
	v_lshlrev_b32_e32 v32, 1, v32
	v_and_b32_e32 v185, 32, v32
	v_lshlrev_b32_e32 v35, 8, v180
	s_movk_i32 s28, 0xc0
	v_add_u32_e32 v32, 0, v185
	v_and_or_b32 v186, v33, s28, v35
	s_and_b32 s1, s34, 0x3fffffc0
	v_add3_u32 v193, v32, v183, v186
	v_max3_f32 v32, v0, v1, v16
	s_lshl_b32 s1, s1, 2
	v_max3_f32 v33, v2, v3, v17
	v_max3_f32 v32, v32, v18, v19
	s_add_i32 s41, s1, 0
	v_max3_f32 v32, v32, v4, v5
	v_max3_f32 v33, v33, v6, v7
	s_add_u32 s28, s8, 0x60000
	v_max3_f32 v32, v32, v20, v21
	v_max3_f32 v33, v33, v22, v23
	s_waitcnt vmcnt(0) lgkmcnt(0)
	s_barrier
	s_cselect_b32 s101, 1, 0
	v_readfirstlane_b32 s100, v181
	s_cmp_lg_u32 s100, 0
	s_cbranch_scc1 .Lmy_fox_nopub
	v_readfirstlane_b32 s100, v201
	v_mov_b32_e32 v246, 0x1c9f0
	v_mov_b32_e32 v247, s100
	ds_write_b32 v246, v247
.Lmy_fox_nopub:
	s_cmp_lg_u32 s101, 0
	s_addc_u32 s29, s9, 0
	v_max3_f32 v32, v32, v8, v9
	v_max3_f32 v33, v33, v10, v11
	s_mov_b32 s1, m0
	s_mov_b32 m0, s89
	s_nop 0
	global_load_lds_dwordx4 v190, s[28:29]
	s_mov_b32 m0, s1
	s_add_u32 s28, s10, 0x20000
	v_max3_f32 v32, v32, v24, v25
	v_max3_f32 v33, v33, v26, v27
	s_addc_u32 s29, s11, 0
	v_max3_f32 v32, v32, v12, v13
	v_max3_f32 v33, v33, v14, v15
	s_cmp_lg_u32 0, -1
	v_max3_f32 v32, v32, v28, v29
	v_max3_f32 v33, v33, v30, v31
	s_cselect_b32 s1, 0, 0
	v_max_f32_e32 v32, v32, v33
	s_add_i32 s1, s1, s31
	v_mov_b32_e32 v33, v32
	s_nop 1
	v_permlane32_swap_b32_e32 v32, v33
	v_max_f32_e32 v32, v32, v33
	s_add_i32 s1, s1, 0x8000
	s_mov_b32 s31, m0
	s_mov_b32 m0, s1
	s_nop 0
	global_load_lds_dwordx4 v191, s[28:29]
	s_mov_b32 m0, s31
	v_xor_b32_e32 v33, 0x80000000, v34
	v_add_f32_e32 v32, v33, v32
	ds_read_b128 v[162:165], v192 offset:8192
	ds_read_b128 v[158:161], v192 offset:8704
	ds_read_b128 v[154:157], v192 offset:10240
	ds_read_b128 v[150:153], v192 offset:10752
	ds_read_b128 v[146:149], v192 offset:12288
	ds_read_b128 v[142:145], v192 offset:12800
	ds_read_b128 v[138:141], v192 offset:14336
	ds_read_b128 v[134:137], v192 offset:14848
	v_xor_b32_e32 v32, 0x80000000, v32
	v_cvt_pk_bf16_f32 v34, v32, 0
	v_lshlrev_b32_e32 v34, 16, v34
	v_sub_f32_e32 v35, v32, v34
	s_waitcnt vmcnt(2) lgkmcnt(0)
	s_barrier
	s_mov_b32 s30, 1
	v_cvt_pk_bf16_f32 v194, v32, v35
	v_and_b32_e32 v32, 0xffff0000, v194
	v_add_f32_e32 v32, v34, v32
	s_mov_b32 s55, 0
	v_xor_b32_e32 v188, 0x80000000, v32
	v_sub_f32_e32 v32, v188, v33
	s_cmp_lt_i32 s78, 7
	v_sub_f32_e32 v0, v0, v32
	v_sub_f32_e32 v16, v16, v32
	v_sub_f32_e32 v1, v1, v32
	v_sub_f32_e32 v17, v17, v32
	v_sub_f32_e32 v2, v2, v32
	v_sub_f32_e32 v18, v18, v32
	v_sub_f32_e32 v3, v3, v32
	v_sub_f32_e32 v19, v19, v32
	v_sub_f32_e32 v4, v4, v32
	v_sub_f32_e32 v20, v20, v32
	v_sub_f32_e32 v5, v5, v32
	v_sub_f32_e32 v21, v21, v32
	v_sub_f32_e32 v6, v6, v32
	v_sub_f32_e32 v22, v22, v32
	v_sub_f32_e32 v7, v7, v32
	v_sub_f32_e32 v23, v23, v32
	v_sub_f32_e32 v8, v8, v32
	v_sub_f32_e32 v24, v24, v32
	v_sub_f32_e32 v9, v9, v32
	v_sub_f32_e32 v25, v25, v32
	v_sub_f32_e32 v10, v10, v32
	v_sub_f32_e32 v26, v26, v32
	v_sub_f32_e32 v11, v11, v32
	v_sub_f32_e32 v27, v27, v32
	v_sub_f32_e32 v12, v12, v32
	v_sub_f32_e32 v28, v28, v32
	v_sub_f32_e32 v13, v13, v32
	v_sub_f32_e32 v29, v29, v32
	v_sub_f32_e32 v14, v14, v32
	v_sub_f32_e32 v30, v30, v32
	v_sub_f32_e32 v15, v15, v32
	v_sub_f32_e32 v31, v31, v32
	s_nop 0
	v_exp_f32_e32 v48, v0
	v_exp_f32_e32 v49, v1
	v_exp_f32_e32 v50, v2
	v_exp_f32_e32 v51, v3
	v_exp_f32_e32 v52, v4
	v_exp_f32_e32 v53, v5
	v_exp_f32_e32 v54, v6
	v_exp_f32_e32 v55, v7
	v_exp_f32_e32 v56, v8
	v_exp_f32_e32 v57, v9
	v_exp_f32_e32 v58, v10
	v_exp_f32_e32 v59, v11
	v_exp_f32_e32 v60, v12
	v_exp_f32_e32 v61, v13
	v_exp_f32_e32 v62, v14
	v_exp_f32_e32 v63, v15
	v_exp_f32_e32 v32, v16
	v_exp_f32_e32 v33, v17
	v_exp_f32_e32 v34, v18
	v_exp_f32_e32 v35, v19
	v_exp_f32_e32 v36, v20
	v_exp_f32_e32 v37, v21
	v_exp_f32_e32 v38, v22
	v_exp_f32_e32 v39, v23
	v_exp_f32_e32 v40, v24
	v_exp_f32_e32 v41, v25
	v_exp_f32_e32 v42, v26
	v_exp_f32_e32 v43, v27
	v_exp_f32_e32 v44, v28
	v_exp_f32_e32 v45, v29
	v_exp_f32_e32 v46, v30
	v_exp_f32_e32 v47, v31
	s_cbranch_scc1 .LBB0_302
	s_add_u32 s10, s10, 0x60000
	s_addc_u32 s11, s11, 0
	v_mov_b32_e32 v14, v101
	v_mov_b32_e32 v15, v101
	s_add_u32 s30, s8, 0xa0000
	v_readlane_b32 s1, v243, 50
	v_mov_b32_e32 v0, v101
	v_mov_b32_e32 v1, v101
	v_mov_b32_e32 v2, v101
	v_mov_b32_e32 v3, v101
	v_mov_b32_e32 v4, v101
	v_mov_b32_e32 v5, v101
	v_mov_b32_e32 v6, v101
	v_mov_b32_e32 v7, v101
	v_mov_b32_e32 v8, v101
	v_mov_b32_e32 v9, v101
	v_mov_b32_e32 v10, v101
	v_mov_b32_e32 v11, v101
	v_mov_b32_e32 v12, v101
	v_mov_b32_e32 v13, v101
	v_mov_b64_e32 v[30:31], v[14:15]
	v_add_u32_e32 v65, s41, v170
	s_addc_u32 s31, s9, 0
	v_add_u32_e32 v171, s1, v170
	s_mov_b32 s60, 0
	s_movk_i32 s55, 0x4000
	s_movk_i32 s85, 0x2000
	v_mov_b32_e32 v64, 0
	s_mov_b32 s51, 6
	v_mov_b64_e32 v[28:29], v[12:13]
	v_mov_b64_e32 v[26:27], v[10:11]
	v_mov_b64_e32 v[24:25], v[8:9]
	v_mov_b64_e32 v[22:23], v[6:7]
	v_mov_b64_e32 v[20:21], v[4:5]
	v_mov_b64_e32 v[18:19], v[2:3]
	v_mov_b64_e32 v[16:17], v[0:1]
